# attention K/V staging: removed four per-trip vmcnt(0) waits that serialized the five staging trips (store phase already waits before its first LDS write)
# speedup vs baseline: 1.0078x; 1.0078x over previous
.LBB0_119:
	v_add_u32_e32 v18, s35, v118
	v_readlane_b32 s24, v254, 29
	v_cmp_lt_i32_e32 vcc, -1, v18
	v_readlane_b32 s25, v254, 30
	s_and_b64 s[26:27], s[24:25], vcc
	v_mov_b32_e32 v13, 0
	v_mov_b32_e32 v12, 0
	v_mov_b32_e32 v11, 0
	v_mov_b32_e32 v10, 0
	v_mov_b32_e32 v17, 0
	v_mov_b32_e32 v16, 0
	v_mov_b32_e32 v15, 0
	v_mov_b32_e32 v14, 0
	s_and_saveexec_b64 s[24:25], s[26:27]
	s_cbranch_execz .LBB0_121
	v_add_u32_e32 v10, s31, v18
	v_ashrrev_i32_e32 v11, 31, v10
	v_lshlrev_b64 v[10:11], 9, v[10:11]
	v_lshl_or_b32 v10, v42, 1, v10
	v_lshl_add_u64 v[12:13], s[60:61], 0, v[10:11]
	v_lshl_add_u64 v[10:11], s[58:59], 0, v[10:11]
	global_load_dwordx4 v[14:17], v[10:11], off
	s_nop 0
	global_load_dwordx4 v[10:13], v[12:13], off

.LBB0_123:
	v_add_u32_e32 v26, s35, v119
	v_readlane_b32 s24, v254, 35
	v_cmp_lt_i32_e32 vcc, -1, v26
	v_readlane_b32 s25, v254, 36
	s_and_b64 s[26:27], s[24:25], vcc
	v_mov_b32_e32 v21, 0
	v_mov_b32_e32 v20, 0
	v_mov_b32_e32 v19, 0
	v_mov_b32_e32 v18, 0
	v_mov_b32_e32 v25, 0
	v_mov_b32_e32 v24, 0
	v_mov_b32_e32 v23, 0
	v_mov_b32_e32 v22, 0
	s_and_saveexec_b64 s[24:25], s[26:27]
	s_cbranch_execz .LBB0_125
	v_add_u32_e32 v18, s31, v26
	v_ashrrev_i32_e32 v19, 31, v18
	v_lshlrev_b64 v[18:19], 9, v[18:19]
	v_lshl_or_b32 v18, v42, 1, v18
	v_lshl_add_u64 v[20:21], s[60:61], 0, v[18:19]
	v_lshl_add_u64 v[18:19], s[58:59], 0, v[18:19]
	global_load_dwordx4 v[22:25], v[18:19], off
	s_nop 0
	global_load_dwordx4 v[18:21], v[20:21], off

.LBB0_127:
	v_add_u32_e32 v34, s35, v120
	v_readlane_b32 s24, v254, 51
	v_cmp_lt_i32_e32 vcc, -1, v34
	v_readlane_b32 s25, v254, 52
	s_and_b64 s[26:27], s[24:25], vcc
	v_mov_b32_e32 v29, 0
	v_mov_b32_e32 v28, 0
	v_mov_b32_e32 v27, 0
	v_mov_b32_e32 v26, 0
	v_mov_b32_e32 v33, 0
	v_mov_b32_e32 v32, 0
	v_mov_b32_e32 v31, 0
	v_mov_b32_e32 v30, 0
	s_and_saveexec_b64 s[24:25], s[26:27]
	s_cbranch_execz .LBB0_129
	v_add_u32_e32 v26, s31, v34
	v_ashrrev_i32_e32 v27, 31, v26
	v_lshlrev_b64 v[26:27], 9, v[26:27]
	v_lshl_or_b32 v26, v42, 1, v26
	v_lshl_add_u64 v[28:29], s[60:61], 0, v[26:27]
	v_lshl_add_u64 v[26:27], s[58:59], 0, v[26:27]
	global_load_dwordx4 v[30:33], v[26:27], off
	s_nop 0
	global_load_dwordx4 v[26:29], v[28:29], off

.LBB0_131:
	v_add_u32_e32 v43, s35, v121
	v_readlane_b32 s22, v254, 57
	v_cmp_lt_i32_e32 vcc, -1, v43
	v_readlane_b32 s23, v254, 58
	s_and_b64 s[24:25], s[22:23], vcc
	v_mov_b32_e32 v37, 0
	v_mov_b32_e32 v36, 0
	v_mov_b32_e32 v35, 0
	v_mov_b32_e32 v34, 0
	v_mov_b32_e32 v41, 0
	v_mov_b32_e32 v40, 0
	v_mov_b32_e32 v39, 0
	v_mov_b32_e32 v38, 0
	s_and_saveexec_b64 s[22:23], s[24:25]
	s_cbranch_execz .LBB0_133
	v_add_u32_e32 v34, s31, v43
	v_ashrrev_i32_e32 v35, 31, v34
	v_lshlrev_b64 v[34:35], 9, v[34:35]
	v_lshl_or_b32 v34, v42, 1, v34
	v_lshl_add_u64 v[36:37], s[60:61], 0, v[34:35]
	v_lshl_add_u64 v[34:35], s[58:59], 0, v[34:35]
	global_load_dwordx4 v[38:41], v[34:35], off
	s_nop 0
	global_load_dwordx4 v[34:37], v[36:37], off
